# stack3 + leading waves issue first QK K-fragment LDS reads before their LDS-DMA block
# baseline (speedup 1.0000x reference)
.LBB0_717:
	s_add_i32 s53, s55, 1
	s_mov_b32 s52, s47
	s_mov_b32 s47, s54
	s_and_b64 vcc, exec, s[4:5]
	s_cbranch_vccnz .Lattn_lag
	s_bitcmp1_b32 s55, 0
	s_cselect_b32 s56, 0x6000, 0
	v_add_u32_e32 v0, s56, v165
	ds_read_b128 v[114:117], v0
	ds_read_b128 v[118:121], v0 offset:1024
	ds_read_b128 v[122:125], v0 offset:6144
	ds_read_b128 v[126:129], v0 offset:7168
	ds_read_b128 v[130:133], v0 offset:12288
	ds_read_b128 v[134:137], v0 offset:13312
	ds_read_b128 v[138:141], v0 offset:18432
	ds_read_b128 v[142:145], v0 offset:19456
	s_cmp_ge_u32 s53, s43
	s_cbranch_scc1 .LBB0_724
	s_bitcmp1_b32 s53, 0
	s_cselect_b32 s54, 0x6000, 0
	s_add_i32 s54, s54, 0
	v_lshl_add_u64 v[250:251], v[180:181], 0, v[166:167]
	s_add_i32 m0, s54, s23
	s_nop 0
	global_load_lds_dwordx4 v[250:251], off
	v_lshl_add_u64 v[250:251], v[178:179], 0, v[166:167]
	s_add_i32 m0, s54, s24
	s_nop 0
	global_load_lds_dwordx4 v[250:251], off
	s_add_i32 m0, s54, s25
	s_lshl_b32 s54, s44, 14
	s_add_i32 s54, s54, 0
	v_lshl_add_u64 v[250:251], v[176:177], 0, v[166:167]
	s_add_i32 s56, s54, s23
	global_load_lds_dwordx4 v[250:251], off
	v_lshl_add_u64 v[250:251], v[182:183], 0, v[166:167]
	s_add_i32 m0, s56, 0xc000
	s_add_i32 s54, s54, s24
	global_load_lds_dwordx4 v[250:251], off
	v_lshl_add_u64 v[250:251], v[184:185], 0, v[166:167]
	s_add_i32 m0, s54, 0xc000
	s_nop 0
	global_load_lds_dwordx4 v[250:251], off
	s_andn2_b64 vcc, exec, s[4:5]
	s_cbranch_vccz .LBB0_725
.LBB0_719:
	s_lshl_b32 s4, s47, 14
	s_add_i32 s54, s4, 0
	s_cmp_gt_i32 s42, s45
	s_cbranch_scc1 .LBB0_726
	s_branch .Lattn_qk_mfma

.Lattn_qk_mfma:
	s_waitcnt lgkmcnt(7)
	v_mfma_f32_16x16x32_bf16 v[190:193], v[114:117], v[42:45], 0
	v_mfma_f32_16x16x32_bf16 v[114:117], v[114:117], v[66:69], 0
	s_waitcnt lgkmcnt(5)
	v_mfma_f32_16x16x32_bf16 v[194:197], v[122:125], v[42:45], 0
	v_mfma_f32_16x16x32_bf16 v[122:125], v[122:125], v[66:69], 0
	s_waitcnt lgkmcnt(3)
	v_mfma_f32_16x16x32_bf16 v[198:201], v[130:133], v[42:45], 0
	v_mfma_f32_16x16x32_bf16 v[130:133], v[130:133], v[66:69], 0
	s_waitcnt lgkmcnt(1)
	v_mfma_f32_16x16x32_bf16 v[202:205], v[138:141], v[42:45], 0
	v_mfma_f32_16x16x32_bf16 v[138:141], v[138:141], v[66:69], 0
	ds_read_b128 v[206:209], v0 offset:2048
	ds_read_b128 v[240:243], v0 offset:8192
	ds_read_b128 v[244:247], v0 offset:14336
	ds_read_b128 v[248:251], v0 offset:20480
	s_waitcnt lgkmcnt(4)
	v_mfma_f32_16x16x32_bf16 v[190:193], v[118:121], v[46:49], v[190:193]
	v_mfma_f32_16x16x32_bf16 v[114:117], v[118:121], v[74:77], v[114:117]
	v_mfma_f32_16x16x32_bf16 v[118:121], v[126:129], v[46:49], v[194:197]
	v_mfma_f32_16x16x32_bf16 v[122:125], v[126:129], v[74:77], v[122:125]
	v_mfma_f32_16x16x32_bf16 v[126:129], v[134:137], v[46:49], v[198:201]
	v_mfma_f32_16x16x32_bf16 v[130:133], v[134:137], v[74:77], v[130:133]
	v_mfma_f32_16x16x32_bf16 v[134:137], v[142:145], v[46:49], v[202:205]
	v_mfma_f32_16x16x32_bf16 v[138:141], v[142:145], v[74:77], v[138:141]
	ds_read_b128 v[142:145], v0 offset:3072
	ds_read_b128 v[194:197], v0 offset:9216
	ds_read_b128 v[198:201], v0 offset:15360
	ds_read_b128 v[202:205], v0 offset:21504
	s_waitcnt lgkmcnt(4)
	v_mfma_f32_16x16x32_bf16 v[114:117], v[206:209], v[78:81], v[114:117]
	v_mfma_f32_16x16x32_bf16 v[118:121], v[240:243], v[50:53], v[118:121]
	v_mfma_f32_16x16x32_bf16 v[122:125], v[240:243], v[78:81], v[122:125]
	v_mfma_f32_16x16x32_bf16 v[126:129], v[244:247], v[50:53], v[126:129]
	v_mfma_f32_16x16x32_bf16 v[130:133], v[244:247], v[78:81], v[130:133]
	v_mfma_f32_16x16x32_bf16 v[134:137], v[248:251], v[50:53], v[134:137]
	v_mfma_f32_16x16x32_bf16 v[138:141], v[248:251], v[78:81], v[138:141]
	v_mfma_f32_16x16x32_bf16 v[190:193], v[206:209], v[50:53], v[190:193]
	ds_read_b128 v[206:209], v0 offset:4096
	ds_read_b128 v[240:243], v0 offset:10240
	ds_read_b128 v[244:247], v0 offset:16384
	ds_read_b128 v[248:251], v0 offset:22528
	s_waitcnt lgkmcnt(4)
	v_mfma_f32_16x16x32_bf16 v[114:117], v[142:145], v[82:85], v[114:117]
	v_mfma_f32_16x16x32_bf16 v[118:121], v[194:197], v[54:57], v[118:121]
	v_mfma_f32_16x16x32_bf16 v[122:125], v[194:197], v[82:85], v[122:125]
	v_mfma_f32_16x16x32_bf16 v[126:129], v[198:201], v[54:57], v[126:129]
	v_mfma_f32_16x16x32_bf16 v[130:133], v[198:201], v[82:85], v[130:133]
	v_mfma_f32_16x16x32_bf16 v[134:137], v[202:205], v[54:57], v[134:137]
	v_mfma_f32_16x16x32_bf16 v[138:141], v[202:205], v[82:85], v[138:141]
	v_mfma_f32_16x16x32_bf16 v[190:193], v[142:145], v[54:57], v[190:193]
	ds_read_b128 v[194:197], v0 offset:5120
	ds_read_b128 v[198:201], v0 offset:11264
	ds_read_b128 v[202:205], v0 offset:17408
	ds_read_b128 v[220:223], v0 offset:23552
	s_waitcnt lgkmcnt(4)
	v_mfma_f32_16x16x32_bf16 v[142:145], v[206:209], v[58:61], v[190:193]
	v_mfma_f32_16x16x32_bf16 v[114:117], v[206:209], v[86:89], v[114:117]
	v_mfma_f32_16x16x32_bf16 v[118:121], v[240:243], v[58:61], v[118:121]
	v_mfma_f32_16x16x32_bf16 v[122:125], v[240:243], v[86:89], v[122:125]
	v_mfma_f32_16x16x32_bf16 v[126:129], v[244:247], v[58:61], v[126:129]
	v_mfma_f32_16x16x32_bf16 v[190:193], v[244:247], v[86:89], v[130:133]
	v_mfma_f32_16x16x32_bf16 v[206:209], v[248:251], v[58:61], v[134:137]
	v_mfma_f32_16x16x32_bf16 v[240:243], v[248:251], v[86:89], v[138:141]
	s_waitcnt lgkmcnt(0)
	v_mfma_f32_16x16x32_bf16 v[142:145], v[194:197], v[62:65], v[142:145]
	v_mfma_f32_16x16x32_bf16 v[134:137], v[194:197], v[94:97], v[114:117]
	v_mfma_f32_16x16x32_bf16 v[138:141], v[198:201], v[62:65], v[118:121]
	v_mfma_f32_16x16x32_bf16 v[130:133], v[198:201], v[94:97], v[122:125]
	v_mfma_f32_16x16x32_bf16 v[118:121], v[202:205], v[62:65], v[126:129]
	v_mfma_f32_16x16x32_bf16 v[126:129], v[202:205], v[94:97], v[190:193]
	v_mfma_f32_16x16x32_bf16 v[114:117], v[220:223], v[62:65], v[206:209]
	v_mfma_f32_16x16x32_bf16 v[122:125], v[220:223], v[94:97], v[240:243]
	s_cmp_lt_u32 s55, s46
	s_cbranch_scc1 .LBB0_722
	v_add_u32_e32 v190, s42, v231
	v_mov_b32_e32 v0, s63
	v_cmp_gt_i32_e32 vcc, v190, v237
	v_cmp_lt_i32_e64 s[4:5], v190, v237
	v_add_u32_e32 v191, 2, v190
	v_cndmask_b32_e32 v0, v142, v0, vcc
	v_cndmask_b32_e64 v142, v0, v142, s[4:5]
	v_cndmask_b32_e64 v143, v224, v143, s[4:5]
	v_cmp_le_i32_e64 s[4:5], v191, v237
	v_add_u32_e32 v192, 3, v190
	v_add_u32_e32 v193, 16, v190
	v_cndmask_b32_e64 v144, v224, v144, s[4:5]
	v_cmp_le_i32_e64 s[4:5], v192, v237
	v_mov_b32_e32 v0, s63
	v_add_u32_e32 v194, 18, v190
	v_cndmask_b32_e64 v145, v224, v145, s[4:5]
	v_cmp_gt_i32_e64 s[4:5], v193, v237
	v_add_u32_e32 v193, 17, v190
	v_add_u32_e32 v195, 19, v190
	v_cndmask_b32_e64 v138, v138, v0, s[4:5]
	v_cmp_le_i32_e64 s[4:5], v193, v237
	v_add_u32_e32 v196, 32, v190
	v_add_u32_e32 v197, 33, v190
	v_cndmask_b32_e64 v139, v224, v139, s[4:5]
	v_cmp_le_i32_e64 s[4:5], v194, v237
	v_add_u32_e32 v198, 34, v190
	v_add_u32_e32 v199, 35, v190
	v_cndmask_b32_e64 v140, v224, v140, s[4:5]
	v_cmp_le_i32_e64 s[4:5], v195, v237
	v_add_u32_e32 v200, 48, v190
	v_add_u32_e32 v201, 49, v190
	v_cndmask_b32_e64 v141, v224, v141, s[4:5]
	v_cmp_gt_i32_e64 s[4:5], v196, v237
	v_add_u32_e32 v202, 50, v190
	v_add_u32_e32 v203, 51, v190
	v_cndmask_b32_e64 v118, v118, v0, s[4:5]
	v_cmp_le_i32_e64 s[4:5], v197, v237
	s_nop 1
	v_cndmask_b32_e64 v119, v224, v119, s[4:5]
	v_cmp_le_i32_e64 s[4:5], v198, v237
	s_nop 1
	v_cndmask_b32_e64 v120, v224, v120, s[4:5]
	v_cmp_le_i32_e64 s[4:5], v199, v237
	s_nop 1
	v_cndmask_b32_e64 v121, v224, v121, s[4:5]
	v_cmp_gt_i32_e64 s[4:5], v200, v237
	s_nop 1
	v_cndmask_b32_e64 v114, v114, v0, s[4:5]
	v_cmp_le_i32_e64 s[4:5], v201, v237
	s_nop 1
	v_cndmask_b32_e64 v115, v224, v115, s[4:5]
	v_cmp_le_i32_e64 s[4:5], v202, v237
	s_nop 1
	v_cndmask_b32_e64 v116, v224, v116, s[4:5]
	v_cmp_le_i32_e64 s[4:5], v203, v237
	s_nop 1
	v_cndmask_b32_e64 v117, v224, v117, s[4:5]
	v_cmp_gt_i32_e64 s[4:5], v190, v238
	s_nop 1
	v_cndmask_b32_e64 v0, v134, v0, s[4:5]
	v_cmp_lt_i32_e64 s[4:5], v190, v238
	s_nop 1
	v_cndmask_b32_e64 v134, v0, v134, s[4:5]
	v_mov_b32_e32 v0, s63
	v_cndmask_b32_e32 v130, v130, v0, vcc
	v_cmp_le_i32_e32 vcc, v193, v238
	v_cndmask_b32_e64 v135, v224, v135, s[4:5]
	v_cmp_le_i32_e64 s[4:5], v191, v238
	v_cndmask_b32_e32 v131, v224, v131, vcc
	v_cmp_le_i32_e32 vcc, v194, v238
	v_cndmask_b32_e64 v136, v224, v136, s[4:5]
	v_cmp_le_i32_e64 s[4:5], v192, v238
	v_cndmask_b32_e32 v132, v224, v132, vcc
	v_cmp_le_i32_e32 vcc, v195, v238
	v_cndmask_b32_e64 v137, v224, v137, s[4:5]
	s_nop 0
	v_cndmask_b32_e32 v133, v224, v133, vcc
	v_cmp_gt_i32_e32 vcc, v196, v238
	s_nop 1
	v_cndmask_b32_e32 v126, v126, v0, vcc
	v_cmp_le_i32_e32 vcc, v197, v238
	s_nop 1
	v_cndmask_b32_e32 v127, v224, v127, vcc
	v_cmp_le_i32_e32 vcc, v198, v238
	s_nop 1
	v_cndmask_b32_e32 v128, v224, v128, vcc
	v_cmp_le_i32_e32 vcc, v199, v238
	s_nop 1
	v_cndmask_b32_e32 v129, v224, v129, vcc
	v_cmp_gt_i32_e32 vcc, v200, v238
	s_nop 1
	v_cndmask_b32_e32 v122, v122, v0, vcc
	v_cmp_le_i32_e32 vcc, v201, v238
	s_nop 1
	v_cndmask_b32_e32 v123, v224, v123, vcc
	v_cmp_le_i32_e32 vcc, v202, v238
	s_nop 1
	v_cndmask_b32_e32 v124, v224, v124, vcc
	v_cmp_le_i32_e32 vcc, v203, v238
	s_nop 1
	v_cndmask_b32_e32 v125, v224, v125, vcc
